# stagger barrier for waves 4-7 moved to just before the PV reads (site B) instead of after QK
# speedup vs baseline: 1.0045x; 1.0003x over previous
; DI s16x4 vtr(const LAS unsigned char* p) { return __builtin_bit_cast(s16x4, __builtin_amdgcn_ds_read_tr16_b64_v4i16((LAS v4i16_t*)p)); }
; #define MFMA32(a, b, c) __builtin_amdgcn_mfma_f32_32x32x16_bf16((a), (b), (c), 0, 0, 0)
; template <int S> DI bf16x8 pack_step(const f32x16& x) { u32x4 p; p.x = pk2(x[8 * S], x[8 * S + 1]); p.y = pk2(x[8 * S + 2], x[8 * S + 3]); p.z = pk2(x[8 * S + 4], x[8 * S + 5]); p.w = pk2(x[8 * S + 6], x[8 * S + 7]); return __builtin_bit_cast(bf16x8, p); }
; DI float ex2(float x) { return __builtin_amdgcn_exp2f(x); }
; template <bool NEAR, int MASK>
; DI void nsa_tile2(f32x16 (&O)[2], float& l, float& inited, f32x16& negm, const LAS unsigned char* Kb, const LAS unsigned char* Vb, const int (&ka)[4], const int (&va)[4], const bf16x8 (&qf)[4],
;                   const LAS float* lutp, float c31, int dlim, bool tok) {
;     ...
;     float ls = 0.f;
; #pragma unroll
;     for (int rb = 0; rb < 2; ++rb)
; #pragma unroll
;         for (int reg = 0; reg < 16; ++reg) { const float p = ex2(S[rb][reg]); S[rb][reg] = p; ls += p; }
;     ls = tok ? ls : 0.f;
;     l += ls;
;     const unsigned pmask = tok ? 0xffffffffu : 0u;
; #pragma unroll
;     for (int rb = 0; rb < 2; ++rb) {
;         u32x4 pa = __builtin_bit_cast(u32x4, pack_step<0>(S[rb])), pb = __builtin_bit_cast(u32x4, pack_step<1>(S[rb]));
;         pa.x &= pmask; pa.y &= pmask; pa.z &= pmask; pa.w &= pmask; pb.x &= pmask; pb.y &= pmask; pb.z &= pmask; pb.w &= pmask;
; #pragma unroll
;         for (int s = 0; s < 2; ++s)
; #pragma unroll
;             for (int db = 0; db < 2; ++db) {
;                 const s16x4 lo = vtr(Vb + va[db] + rb * 4096 + s * 2048), hi = vtr(Vb + va[2 + db] + rb * 4096 + s * 2048);
;                 const bf16x8 vf = __builtin_shufflevector(lo, hi, 0, 1, 2, 3, 4, 5, 6, 7);
;                 O[db] = MFMA32(vf, __builtin_bit_cast(bf16x8, s == 0 ? pa : pb), O[db]); }
.LBB0_2048:
	v_exp_f32_e32 v9, v9
	v_exp_f32_e32 v8, v8
	v_exp_f32_e32 v11, v11
	v_exp_f32_e32 v10, v10
	v_add_f32_e32 v203, 0, v9
	v_exp_f32_e32 v130, v130
	v_add_f32_e32 v203, v8, v203
	v_exp_f32_e32 v17, v17
	v_add_f32_e32 v203, v11, v203
	v_exp_f32_e32 v132, v132
	v_add_f32_e32 v203, v10, v203
	v_exp_f32_e32 v131, v131
	v_add_f32_e32 v203, v130, v203
	v_add_f32_e32 v203, v17, v203
	v_add_f32_e32 v203, v132, v203
	v_add_f32_e32 v203, v131, v203
	v_cvt_pk_bf16_f32 v8, v9, v8
	v_cvt_pk_bf16_f32 v9, v11, v10
	v_cvt_pk_bf16_f32 v10, v130, v17
	v_cvt_pk_bf16_f32 v11, v132, v131
	v_add_u32_e32 v17, s20, v227
	v_add_u32_e32 v130, s20, v229
	v_add_u32_e32 v131, s20, v228
	s_cmp_eq_u32 s98, 0
	s_cbranch_scc1 .Lnsa_nomid_a
	s_waitcnt vmcnt(0) lgkmcnt(0)
	s_barrier
	s_mov_b32 s99, 1
.Lnsa_nomid_a:
	ds_read_b64_tr_b16 v[204:205], v17 offset:8192
	ds_read_b64_tr_b16 v[206:207], v130 offset:8192
	ds_read_b64_tr_b16 v[208:209], v131 offset:8192
	v_add_u32_e32 v132, s20, v230
	ds_read_b64_tr_b16 v[210:211], v132 offset:8192
	ds_read_b64_tr_b16 v[212:213], v17 offset:10240
	ds_read_b64_tr_b16 v[236:237], v17 offset:12288
	ds_read_b64_tr_b16 v[240:241], v17 offset:14336
	ds_read_b64_tr_b16 v[214:215], v130 offset:10240
	ds_read_b64_tr_b16 v[238:239], v130 offset:12288
	ds_read_b64_tr_b16 v[242:243], v130 offset:14336
	s_waitcnt lgkmcnt(8)
	v_mfma_f32_32x32x16_bf16 v[50:65], v[204:207], v[8:11], v[50:65]
	v_exp_f32_e32 v140, v140
	v_exp_f32_e32 v137, v137
	v_exp_f32_e32 v192, v192
	v_exp_f32_e32 v141, v141
	v_exp_f32_e32 v196, v196
	v_exp_f32_e32 v193, v193
	v_exp_f32_e32 v199, v199
	s_waitcnt lgkmcnt(6)
	v_mfma_f32_32x32x16_bf16 v[66:81], v[208:211], v[8:11], v[66:81]
	v_exp_f32_e32 v197, v197
	v_add_f32_e32 v203, v140, v203
	ds_read_b64_tr_b16 v[204:205], v131 offset:10240
	ds_read_b64_tr_b16 v[244:245], v131 offset:12288
	ds_read_b64_tr_b16 v[248:249], v131 offset:14336
	ds_read_b64_tr_b16 v[206:207], v132 offset:10240
	ds_read_b64_tr_b16 v[246:247], v132 offset:12288
	ds_read_b64_tr_b16 v[250:251], v132 offset:14336
	v_add_f32_e32 v203, v137, v203
	v_add_f32_e32 v203, v192, v203
	v_cvt_pk_bf16_f32 v8, v140, v137
	v_cvt_pk_bf16_f32 v9, v192, v141
	v_cvt_pk_bf16_f32 v10, v196, v193
	v_cvt_pk_bf16_f32 v11, v199, v197
	v_add_f32_e32 v203, v141, v203
	v_add_f32_e32 v203, v196, v203
	s_waitcnt lgkmcnt(8)
	v_mfma_f32_32x32x16_bf16 v[50:65], v[212:215], v[8:11], v[50:65]
	v_exp_f32_e32 v201, v201
	v_add_f32_e32 v203, v193, v203
	v_exp_f32_e32 v14, v14
	v_add_f32_e32 v203, v199, v203
	v_exp_f32_e32 v13, v13
	v_exp_f32_e32 v12, v12
	v_exp_f32_e32 v16, v16
	s_waitcnt lgkmcnt(2)
	v_mfma_f32_32x32x16_bf16 v[66:81], v[204:207], v[8:11], v[66:81]
	v_exp_f32_e32 v15, v15
	v_exp_f32_e32 v130, v134
	v_exp_f32_e32 v131, v133
	v_add_f32_e32 v203, v197, v203
	v_add_f32_e32 v203, v201, v203
	v_add_f32_e32 v17, v14, v203
	v_add_f32_e32 v17, v13, v17
	v_cvt_pk_bf16_f32 v8, v201, v14
	v_cvt_pk_bf16_f32 v9, v13, v12
	v_cvt_pk_bf16_f32 v10, v16, v15
	v_cvt_pk_bf16_f32 v11, v130, v131
	v_add_f32_e32 v17, v12, v17
	v_add_f32_e32 v17, v16, v17
	v_mfma_f32_32x32x16_bf16 v[50:65], v[236:239], v[8:11], v[50:65]
	v_add_f32_e32 v17, v15, v17
	v_exp_f32_e32 v132, v136
	v_exp_f32_e32 v133, v135
	v_add_f32_e32 v12, v130, v17
	v_exp_f32_e32 v13, v139
	v_exp_f32_e32 v14, v138
	v_exp_f32_e32 v15, v195
	s_waitcnt lgkmcnt(1)
	v_mfma_f32_32x32x16_bf16 v[66:81], v[244:247], v[8:11], v[66:81]
	v_exp_f32_e32 v16, v194
	v_exp_f32_e32 v17, v200
	v_exp_f32_e32 v130, v198
	v_add_f32_e32 v12, v131, v12
	v_add_f32_e32 v12, v132, v12
	v_cvt_pk_bf16_f32 v8, v132, v133
	v_cvt_pk_bf16_f32 v9, v13, v14
	v_cvt_pk_bf16_f32 v10, v15, v16
	v_cvt_pk_bf16_f32 v11, v17, v130
	v_add_f32_e32 v12, v133, v12
	v_add_f32_e32 v12, v13, v12
	v_mfma_f32_32x32x16_bf16 v[50:65], v[240:243], v[8:11], v[50:65]
	v_add_f32_e32 v12, v14, v12
	v_add_f32_e32 v12, v15, v12
	v_add_f32_e32 v12, v16, v12
	v_add_f32_e32 v12, v17, v12
	v_add_f32_e32 v12, v130, v12
	v_add_f32_e32 v16, v202, v12
	s_mov_b64 s[6:7], 0
	s_waitcnt lgkmcnt(0)
	v_mfma_f32_32x32x16_bf16 v[66:81], v[248:251], v[8:11], v[66:81]

; DI s16x4 vtr(const LAS unsigned char* p) { return __builtin_bit_cast(s16x4, __builtin_amdgcn_ds_read_tr16_b64_v4i16((LAS v4i16_t*)p)); }
; #define MFMA32(a, b, c) __builtin_amdgcn_mfma_f32_32x32x16_bf16((a), (b), (c), 0, 0, 0)
; template <int S> DI bf16x8 pack_step(const f32x16& x) { u32x4 p; p.x = pk2(x[8 * S], x[8 * S + 1]); p.y = pk2(x[8 * S + 2], x[8 * S + 3]); p.z = pk2(x[8 * S + 4], x[8 * S + 5]); p.w = pk2(x[8 * S + 6], x[8 * S + 7]); return __builtin_bit_cast(bf16x8, p); }
; DI float ex2(float x) { return __builtin_amdgcn_exp2f(x); }
; template <bool NEAR, int MASK>
; DI void nsa_tile2(f32x16 (&O)[2], float& l, float& inited, f32x16& negm, const LAS unsigned char* Kb, const LAS unsigned char* Vb, const int (&ka)[4], const int (&va)[4], const bf16x8 (&qf)[4],
;                   const LAS float* lutp, float c31, int dlim, bool tok) {
;     ...
;     float ls = 0.f;
; #pragma unroll
;     for (int rb = 0; rb < 2; ++rb)
; #pragma unroll
;         for (int reg = 0; reg < 16; ++reg) { const float p = ex2(S[rb][reg]); S[rb][reg] = p; ls += p; }
;     ls = tok ? ls : 0.f;
;     l += ls;
;     const unsigned pmask = tok ? 0xffffffffu : 0u;
; #pragma unroll
;     for (int rb = 0; rb < 2; ++rb) {
;         u32x4 pa = __builtin_bit_cast(u32x4, pack_step<0>(S[rb])), pb = __builtin_bit_cast(u32x4, pack_step<1>(S[rb]));
;         pa.x &= pmask; pa.y &= pmask; pa.z &= pmask; pa.w &= pmask; pb.x &= pmask; pb.y &= pmask; pb.z &= pmask; pb.w &= pmask;
; #pragma unroll
;         for (int s = 0; s < 2; ++s)
; #pragma unroll
;             for (int db = 0; db < 2; ++db) {
;                 const s16x4 lo = vtr(Vb + va[db] + rb * 4096 + s * 2048), hi = vtr(Vb + va[2 + db] + rb * 4096 + s * 2048);
;                 const bf16x8 vf = __builtin_shufflevector(lo, hi, 0, 1, 2, 3, 4, 5, 6, 7);
;                 O[db] = MFMA32(vf, __builtin_bit_cast(bf16x8, s == 0 ? pa : pb), O[db]); }
.LBB0_2056:
	v_exp_f32_e32 v202, v202
	v_exp_f32_e32 v203, v203
	v_exp_f32_e32 v198, v198
	v_exp_f32_e32 v199, v199
	v_add_f32_e32 v239, 0, v202
	v_exp_f32_e32 v138, v138
	v_add_f32_e32 v239, v203, v239
	v_exp_f32_e32 v139, v139
	v_add_f32_e32 v239, v198, v239
	v_exp_f32_e32 v240, v16
	v_add_f32_e32 v239, v199, v239
	v_exp_f32_e32 v17, v17
	v_add_f32_e32 v239, v138, v239
	v_exp_f32_e32 v204, v204
	v_add_f32_e32 v239, v139, v239
	v_exp_f32_e32 v205, v205
	v_add_f32_e32 v16, v240, v239
	v_exp_f32_e32 v196, v196
	v_add_f32_e32 v16, v17, v16
	v_exp_f32_e32 v197, v197
	v_add_f32_e32 v16, v204, v16
	v_exp_f32_e32 v140, v140
	v_add_f32_e32 v16, v205, v16
	v_exp_f32_e32 v141, v141
	v_exp_f32_e32 v192, v192
	v_exp_f32_e32 v193, v193
	v_add_f32_e32 v16, v196, v16
	v_add_f32_e32 v16, v197, v16
	v_add_f32_e32 v16, v140, v16
	v_add_f32_e32 v16, v141, v16
	v_exp_f32_e32 v239, v194
	v_exp_f32_e32 v241, v195
	v_cvt_pk_bf16_f32 v194, v202, v203
	v_cvt_pk_bf16_f32 v195, v198, v199
	v_cvt_pk_bf16_f32 v17, v240, v17
	v_cvt_pk_bf16_f32 v202, v192, v193
	v_add_f32_e32 v16, v192, v16
	v_cvt_pk_bf16_f32 v198, v138, v139
	v_cvt_pk_bf16_f32 v199, v204, v205
	v_cvt_pk_bf16_f32 v196, v196, v197
	v_cvt_pk_bf16_f32 v197, v140, v141
	v_cndmask_b32_e64 v139, 0, v195, s[2:3]
	v_cndmask_b32_e64 v141, 0, v17, s[2:3]
	v_cndmask_b32_e64 v195, 0, v202, s[2:3]
	v_add_u32_e32 v17, s20, v227
	v_add_u32_e32 v202, s20, v229
	v_add_f32_e32 v16, v193, v16
	v_cndmask_b32_e64 v138, 0, v194, s[2:3]
	v_cndmask_b32_e64 v140, 0, v198, s[2:3]
	v_cndmask_b32_e64 v192, 0, v199, s[2:3]
	v_cndmask_b32_e64 v193, 0, v196, s[2:3]
	v_cndmask_b32_e64 v194, 0, v197, s[2:3]
	s_cmp_eq_u32 s98, 0
	s_cbranch_scc1 .Lnsa_nomid_b
	s_waitcnt vmcnt(0) lgkmcnt(0)
	s_barrier
	s_mov_b32 s99, 1
.Lnsa_nomid_b:
	ds_read_b64_tr_b16 v[196:197], v17 offset:8192
	ds_read_b64_tr_b16 v[198:199], v202 offset:8192
	v_add_u32_e32 v203, s20, v228
	v_add_u32_e32 v204, s20, v230
	s_waitcnt lgkmcnt(0)
	v_mfma_f32_32x32x16_bf16 v[50:65], v[196:199], v[138:141], v[50:65]
	ds_read_b64_tr_b16 v[196:197], v203 offset:8192
	ds_read_b64_tr_b16 v[198:199], v204 offset:8192
	v_exp_f32_e32 v208, v208
	v_exp_f32_e32 v209, v209
	v_exp_f32_e32 v206, v206
	v_exp_f32_e32 v207, v207
	v_exp_f32_e32 v200, v200
	s_waitcnt lgkmcnt(0)
	v_mfma_f32_32x32x16_bf16 v[66:81], v[196:199], v[138:141], v[66:81]
	ds_read_b64_tr_b16 v[138:139], v17 offset:10240
	ds_read_b64_tr_b16 v[140:141], v202 offset:10240
	v_exp_f32_e32 v201, v201
	v_exp_f32_e32 v214, v214
	v_exp_f32_e32 v215, v215
	v_exp_f32_e32 v212, v212
	v_exp_f32_e32 v213, v213
	v_exp_f32_e32 v210, v210
	s_waitcnt lgkmcnt(0)
	v_mfma_f32_32x32x16_bf16 v[50:65], v[138:141], v[192:195], v[50:65]
	ds_read_b64_tr_b16 v[138:139], v203 offset:10240
	ds_read_b64_tr_b16 v[140:141], v204 offset:10240
	v_exp_f32_e32 v211, v211
	v_exp_f32_e32 v216, v216
	v_exp_f32_e32 v217, v217
	v_cvt_pk_bf16_f32 v196, v214, v215
	v_cvt_pk_bf16_f32 v197, v212, v213
	v_cvt_pk_bf16_f32 v198, v210, v211
	s_waitcnt lgkmcnt(0)
	v_mfma_f32_32x32x16_bf16 v[66:81], v[138:141], v[192:195], v[66:81]
	v_cvt_pk_bf16_f32 v138, v208, v209
	v_cvt_pk_bf16_f32 v139, v206, v207
	v_cvt_pk_bf16_f32 v140, v200, v201
	v_cvt_pk_bf16_f32 v141, v239, v241
	v_cvt_pk_bf16_f32 v199, v216, v217
	v_cndmask_b32_e64 v192, 0, v138, s[2:3]
	v_cndmask_b32_e64 v193, 0, v139, s[2:3]
	v_cndmask_b32_e64 v194, 0, v140, s[2:3]
	v_cndmask_b32_e64 v195, 0, v141, s[2:3]
	v_cndmask_b32_e64 v138, 0, v196, s[2:3]
	v_cndmask_b32_e64 v139, 0, v197, s[2:3]
	v_cndmask_b32_e64 v140, 0, v198, s[2:3]
	v_cndmask_b32_e64 v141, 0, v199, s[2:3]
	ds_read_b64_tr_b16 v[196:197], v17 offset:12288
	ds_read_b64_tr_b16 v[198:199], v202 offset:12288
	s_waitcnt lgkmcnt(0)
	v_mfma_f32_32x32x16_bf16 v[50:65], v[196:199], v[192:195], v[50:65]
	ds_read_b64_tr_b16 v[196:197], v203 offset:12288
	ds_read_b64_tr_b16 v[198:199], v204 offset:12288
	v_add_f32_e32 v16, v208, v16
	v_add_f32_e32 v16, v209, v16
	v_add_f32_e32 v16, v206, v16
	v_add_f32_e32 v16, v207, v16
	v_add_f32_e32 v16, v200, v16
	v_add_f32_e32 v16, v201, v16
	s_waitcnt lgkmcnt(0)
	v_mfma_f32_32x32x16_bf16 v[66:81], v[196:199], v[192:195], v[66:81]
	ds_read_b64_tr_b16 v[192:193], v17 offset:14336
	ds_read_b64_tr_b16 v[194:195], v202 offset:14336
	v_add_f32_e32 v16, v239, v16
	v_add_f32_e32 v16, v241, v16
	v_add_f32_e32 v16, v214, v16
	v_add_f32_e32 v16, v215, v16
	v_add_f32_e32 v16, v212, v16
	v_add_f32_e32 v16, v213, v16
	s_waitcnt lgkmcnt(0)
	v_mfma_f32_32x32x16_bf16 v[50:65], v[192:195], v[138:141], v[50:65]
	ds_read_b64_tr_b16 v[192:193], v203 offset:14336
	ds_read_b64_tr_b16 v[194:195], v204 offset:14336
	v_add_f32_e32 v16, v210, v16
	v_add_f32_e32 v16, v211, v16
	v_add_f32_e32 v16, v216, v16
	v_add_f32_e32 v16, v217, v16
	v_cndmask_b32_e64 v16, 0, v16, s[2:3]
	v_add_f32_e32 v16, v238, v16
	s_waitcnt lgkmcnt(0)
	v_mfma_f32_32x32x16_bf16 v[66:81], v[192:195], v[138:141], v[66:81]
	s_mov_b64 s[0:1], 0

; DI s16x4 vtr(const LAS unsigned char* p) { return __builtin_bit_cast(s16x4, __builtin_amdgcn_ds_read_tr16_b64_v4i16((LAS v4i16_t*)p)); }
; #define MFMA32(a, b, c) __builtin_amdgcn_mfma_f32_32x32x16_bf16((a), (b), (c), 0, 0, 0)
; template <int S> DI bf16x8 pack_step(const f32x16& x) { u32x4 p; p.x = pk2(x[8 * S], x[8 * S + 1]); p.y = pk2(x[8 * S + 2], x[8 * S + 3]); p.z = pk2(x[8 * S + 4], x[8 * S + 5]); p.w = pk2(x[8 * S + 6], x[8 * S + 7]); return __builtin_bit_cast(bf16x8, p); }
; DI float ex2(float x) { return __builtin_amdgcn_exp2f(x); }
; template <bool NEAR, int MASK>
; DI void nsa_tile2(f32x16 (&O)[2], float& l, float& inited, f32x16& negm, const LAS unsigned char* Kb, const LAS unsigned char* Vb, const int (&ka)[4], const int (&va)[4], const bf16x8 (&qf)[4],
;                   const LAS float* lutp, float c31, int dlim, bool tok) {
;     ...
;     float ls = 0.f;
; #pragma unroll
;     for (int rb = 0; rb < 2; ++rb)
; #pragma unroll
;         for (int reg = 0; reg < 16; ++reg) { const float p = ex2(S[rb][reg]); S[rb][reg] = p; ls += p; }
;     ls = tok ? ls : 0.f;
;     l += ls;
;     const unsigned pmask = tok ? 0xffffffffu : 0u;
; #pragma unroll
;     for (int rb = 0; rb < 2; ++rb) {
;         u32x4 pa = __builtin_bit_cast(u32x4, pack_step<0>(S[rb])), pb = __builtin_bit_cast(u32x4, pack_step<1>(S[rb]));
;         pa.x &= pmask; pa.y &= pmask; pa.z &= pmask; pa.w &= pmask; pb.x &= pmask; pb.y &= pmask; pb.z &= pmask; pb.w &= pmask;
; #pragma unroll
;         for (int s = 0; s < 2; ++s)
; #pragma unroll
;             for (int db = 0; db < 2; ++db) {
;                 const s16x4 lo = vtr(Vb + va[db] + rb * 4096 + s * 2048), hi = vtr(Vb + va[2 + db] + rb * 4096 + s * 2048);
;                 const bf16x8 vf = __builtin_shufflevector(lo, hi, 0, 1, 2, 3, 4, 5, 6, 7);
;                 O[db] = MFMA32(vf, __builtin_bit_cast(bf16x8, s == 0 ? pa : pb), O[db]); }
.LBB0_2068:
	v_exp_f32_e32 v56, v68
	v_exp_f32_e32 v57, v66
	v_exp_f32_e32 v58, v67
	v_exp_f32_e32 v16, v16
	v_add_f32_e32 v59, 0, v56
	v_exp_f32_e32 v15, v15
	v_add_f32_e32 v59, v57, v59
	v_exp_f32_e32 v14, v14
	v_add_f32_e32 v59, v58, v59
	v_exp_f32_e32 v60, v69
	v_add_f32_e32 v59, v16, v59
	v_exp_f32_e32 v17, v17
	v_add_f32_e32 v59, v15, v59
	v_exp_f32_e32 v68, v71
	v_add_f32_e32 v59, v14, v59
	v_exp_f32_e32 v69, v70
	v_add_f32_e32 v59, v60, v59
	v_exp_f32_e32 v77, v7
	v_add_f32_e32 v59, v17, v59
	v_exp_f32_e32 v78, v5
	v_add_f32_e32 v59, v68, v59
	v_exp_f32_e32 v79, v6
	v_add_f32_e32 v59, v69, v59
	v_exp_f32_e32 v80, v4
	v_add_f32_e32 v4, v77, v59
	v_exp_f32_e32 v81, v73
	v_add_f32_e32 v4, v78, v4
	v_exp_f32_e32 v98, v72
	v_add_f32_e32 v4, v79, v4
	v_exp_f32_e32 v76, v76
	v_add_f32_e32 v4, v80, v4
	v_exp_f32_e32 v99, v75
	v_cvt_pk_bf16_f32 v5, v58, v16
	v_add_u32_e32 v58, s20, v227
	v_add_u32_e32 v66, s20, v229
	v_add_u32_e32 v70, s20, v228
	v_add_f32_e32 v4, v81, v4
	v_exp_f32_e32 v100, v74
	v_exp_f32_e32 v101, v52
	v_exp_f32_e32 v102, v53
	v_cvt_pk_bf16_f32 v6, v15, v14
	v_cvt_pk_bf16_f32 v7, v60, v17
	s_cmp_eq_u32 s98, 0
	s_cbranch_scc1 .Lnsa_nomid_d
	s_waitcnt vmcnt(0) lgkmcnt(0)
	s_barrier
	s_mov_b32 s99, 1
.Lnsa_nomid_d:
	ds_read_b64_tr_b16 v[14:15], v58 offset:8192
	ds_read_b64_tr_b16 v[16:17], v66 offset:8192
	ds_read_b64_tr_b16 v[52:53], v70 offset:8192
	v_add_f32_e32 v4, v98, v4
	v_add_f32_e32 v4, v76, v4
	v_add_f32_e32 v4, v99, v4
	v_exp_f32_e32 v51, v51
	v_add_f32_e32 v4, v100, v4
	v_add_f32_e32 v4, v101, v4
	v_add_f32_e32 v4, v102, v4
	v_add_f32_e32 v103, v51, v4
	v_cvt_pk_bf16_f32 v4, v56, v57
	v_cndmask_b32_e64 v4, 0, v4, s[2:3]
	v_cndmask_b32_e64 v5, 0, v5, s[2:3]
	v_cndmask_b32_e64 v6, 0, v6, s[2:3]
	v_cndmask_b32_e64 v7, 0, v7, s[2:3]
	v_add_u32_e32 v74, s20, v230
	v_exp_f32_e32 v104, v55
	v_exp_f32_e32 v105, v54
	ds_read_b64_tr_b16 v[54:55], v74 offset:8192
	ds_read_b64_tr_b16 v[56:57], v58 offset:10240
	ds_read_b64_tr_b16 v[60:61], v58 offset:12288
	ds_read_b64_tr_b16 v[64:65], v58 offset:14336
	ds_read_b64_tr_b16 v[58:59], v66 offset:10240
	ds_read_b64_tr_b16 v[62:63], v66 offset:12288
	ds_read_b64_tr_b16 v[66:67], v66 offset:14336
	s_waitcnt lgkmcnt(6)
	v_mfma_f32_32x32x16_bf16 v[34:49], v[52:55], v[4:7], v[34:49]
	v_cvt_pk_bf16_f32 v106, v68, v69
	v_exp_f32_e32 v12, v12
	v_exp_f32_e32 v11, v11
	v_exp_f32_e32 v13, v13
	v_exp_f32_e32 v8, v8
	v_exp_f32_e32 v10, v10
	v_exp_f32_e32 v9, v9
	v_mfma_f32_32x32x16_bf16 v[18:33], v[14:17], v[4:7], v[18:33]
	ds_read_b64_tr_b16 v[14:15], v70 offset:10240
	ds_read_b64_tr_b16 v[68:69], v70 offset:12288
	ds_read_b64_tr_b16 v[72:73], v70 offset:14336
	ds_read_b64_tr_b16 v[16:17], v74 offset:10240
	ds_read_b64_tr_b16 v[70:71], v74 offset:12288
	ds_read_b64_tr_b16 v[74:75], v74 offset:14336
	v_cvt_pk_bf16_f32 v5, v77, v78
	v_cvt_pk_bf16_f32 v6, v79, v80
	v_cvt_pk_bf16_f32 v7, v81, v98
	v_cndmask_b32_e64 v4, 0, v106, s[2:3]
	v_cndmask_b32_e64 v5, 0, v5, s[2:3]
	v_cndmask_b32_e64 v6, 0, v6, s[2:3]
	v_cndmask_b32_e64 v7, 0, v7, s[2:3]
	v_exp_f32_e32 v3, v3
	v_add_f32_e32 v52, v104, v103
	s_waitcnt lgkmcnt(2)
	v_mfma_f32_32x32x16_bf16 v[34:49], v[14:17], v[4:7], v[34:49]
	v_exp_f32_e32 v15, v50
	v_add_f32_e32 v52, v105, v52
	v_add_f32_e32 v52, v12, v52
	v_add_f32_e32 v52, v11, v52
	v_cvt_pk_bf16_f32 v11, v12, v11
	v_add_f32_e32 v14, v13, v52
	v_mov_b32_e32 v235, v232
	v_mfma_f32_32x32x16_bf16 v[18:33], v[56:59], v[4:7], v[18:33]
	v_cvt_pk_bf16_f32 v4, v76, v99
	v_cvt_pk_bf16_f32 v5, v100, v101
	v_cvt_pk_bf16_f32 v6, v102, v51
	v_cvt_pk_bf16_f32 v7, v104, v105
	v_cndmask_b32_e64 v4, 0, v4, s[2:3]
	v_cndmask_b32_e64 v5, 0, v5, s[2:3]
	v_cndmask_b32_e64 v6, 0, v6, s[2:3]
	v_cndmask_b32_e64 v7, 0, v7, s[2:3]
	v_mov_b64_e32 v[112:113], v[96:97]
	v_mov_b64_e32 v[110:111], v[94:95]
	s_waitcnt lgkmcnt(1)
	v_mfma_f32_32x32x16_bf16 v[34:49], v[68:71], v[4:7], v[34:49]
	v_mov_b64_e32 v[108:109], v[92:93]
	v_mov_b64_e32 v[106:107], v[90:91]
	v_mov_b64_e32 v[104:105], v[88:89]
	v_mov_b64_e32 v[102:103], v[86:87]
	v_mov_b64_e32 v[100:101], v[84:85]
	v_mov_b64_e32 v[98:99], v[82:83]
	v_mfma_f32_32x32x16_bf16 v[18:33], v[60:63], v[4:7], v[18:33]
	v_cvt_pk_bf16_f32 v5, v13, v8
	v_cvt_pk_bf16_f32 v6, v10, v9
	v_cvt_pk_bf16_f32 v7, v3, v15
	v_cndmask_b32_e64 v4, 0, v11, s[2:3]
	v_cndmask_b32_e64 v5, 0, v5, s[2:3]
	v_cndmask_b32_e64 v6, 0, v6, s[2:3]
	v_cndmask_b32_e64 v7, 0, v7, s[2:3]
	v_add_f32_e32 v8, v8, v14
	v_add_f32_e32 v8, v10, v8
	s_waitcnt lgkmcnt(0)
	v_mfma_f32_32x32x16_bf16 v[34:49], v[72:75], v[4:7], v[34:49]
	v_add_f32_e32 v8, v9, v8
	v_add_f32_e32 v3, v3, v8
	v_add_f32_e32 v3, v15, v3
	v_cndmask_b32_e64 v3, 0, v3, s[2:3]
	v_add_f32_e32 v16, v231, v3
	v_mfma_f32_32x32x16_bf16 v[18:33], v[64:67], v[4:7], v[18:33]
	s_nop 5
	v_mov_b64_e32 v[80:81], v[48:49]
	v_mov_b64_e32 v[78:79], v[46:47]
	v_mov_b64_e32 v[76:77], v[44:45]
	v_mov_b64_e32 v[74:75], v[42:43]
	v_mov_b64_e32 v[72:73], v[40:41]
	v_mov_b64_e32 v[70:71], v[38:39]
	v_mov_b64_e32 v[68:69], v[36:37]
	v_mov_b64_e32 v[66:67], v[34:35]
	v_mov_b64_e32 v[64:65], v[32:33]
	v_mov_b64_e32 v[62:63], v[30:31]
	v_mov_b64_e32 v[60:61], v[28:29]
	v_mov_b64_e32 v[58:59], v[26:27]
	v_mov_b64_e32 v[56:57], v[24:25]
	v_mov_b64_e32 v[54:55], v[22:23]
	v_mov_b64_e32 v[52:53], v[20:21]
	v_mov_b64_e32 v[50:51], v[18:19]

; DI s16x4 vtr(const LAS unsigned char* p) { return __builtin_bit_cast(s16x4, __builtin_amdgcn_ds_read_tr16_b64_v4i16((LAS v4i16_t*)p)); }
; #define MFMA32(a, b, c) __builtin_amdgcn_mfma_f32_32x32x16_bf16((a), (b), (c), 0, 0, 0)
; template <int S> DI bf16x8 pack_step(const f32x16& x) { u32x4 p; p.x = pk2(x[8 * S], x[8 * S + 1]); p.y = pk2(x[8 * S + 2], x[8 * S + 3]); p.z = pk2(x[8 * S + 4], x[8 * S + 5]); p.w = pk2(x[8 * S + 6], x[8 * S + 7]); return __builtin_bit_cast(bf16x8, p); }
; DI float ex2(float x) { return __builtin_amdgcn_exp2f(x); }
; template <bool NEAR, int MASK>
; DI void nsa_tile2(f32x16 (&O)[2], float& l, float& inited, f32x16& negm, const LAS unsigned char* Kb, const LAS unsigned char* Vb, const int (&ka)[4], const int (&va)[4], const bf16x8 (&qf)[4],
;                   const LAS float* lutp, float c31, int dlim, bool tok) {
;     ...
;     float ls = 0.f;
; #pragma unroll
;     for (int rb = 0; rb < 2; ++rb)
; #pragma unroll
;         for (int reg = 0; reg < 16; ++reg) { const float p = ex2(S[rb][reg]); S[rb][reg] = p; ls += p; }
;     ls = tok ? ls : 0.f;
;     l += ls;
;     const unsigned pmask = tok ? 0xffffffffu : 0u;
; #pragma unroll
;     for (int rb = 0; rb < 2; ++rb) {
;         u32x4 pa = __builtin_bit_cast(u32x4, pack_step<0>(S[rb])), pb = __builtin_bit_cast(u32x4, pack_step<1>(S[rb]));
;         pa.x &= pmask; pa.y &= pmask; pa.z &= pmask; pa.w &= pmask; pb.x &= pmask; pb.y &= pmask; pb.z &= pmask; pb.w &= pmask;
; #pragma unroll
;         for (int s = 0; s < 2; ++s)
; #pragma unroll
;             for (int db = 0; db < 2; ++db) {
;                 const s16x4 lo = vtr(Vb + va[db] + rb * 4096 + s * 2048), hi = vtr(Vb + va[2 + db] + rb * 4096 + s * 2048);
;                 const bf16x8 vf = __builtin_shufflevector(lo, hi, 0, 1, 2, 3, 4, 5, 6, 7);
;                 O[db] = MFMA32(vf, __builtin_bit_cast(bf16x8, s == 0 ? pa : pb), O[db]); }
.LBB0_2075:
	v_exp_f32_e32 v196, v196
	v_exp_f32_e32 v197, v197
	v_exp_f32_e32 v194, v194
	v_exp_f32_e32 v195, v195
	v_add_f32_e32 v199, 0, v196
	v_exp_f32_e32 v192, v192
	v_add_f32_e32 v199, v197, v199
	v_exp_f32_e32 v193, v193
	v_add_f32_e32 v199, v194, v199
	v_exp_f32_e32 v140, v140
	v_add_f32_e32 v199, v195, v199
	v_exp_f32_e32 v141, v141
	v_add_f32_e32 v199, v192, v199
	v_exp_f32_e32 v204, v138
	v_add_f32_e32 v199, v193, v199
	v_exp_f32_e32 v205, v139
	v_add_f32_e32 v138, v140, v199
	v_exp_f32_e32 v199, v136
	v_add_f32_e32 v138, v141, v138
	v_exp_f32_e32 v212, v137
	v_add_f32_e32 v138, v204, v138
	v_exp_f32_e32 v213, v134
	v_add_f32_e32 v138, v205, v138
	v_exp_f32_e32 v214, v135
	v_add_f32_e32 v134, v199, v138
	v_exp_f32_e32 v215, v132
	v_add_f32_e32 v134, v212, v134
	v_exp_f32_e32 v216, v133
	v_add_f32_e32 v134, v213, v134
	v_exp_f32_e32 v217, v130
	v_add_f32_e32 v134, v214, v134
	v_exp_f32_e32 v236, v131
	v_add_f32_e32 v130, v215, v134
	v_exp_f32_e32 v16, v16
	v_add_f32_e32 v130, v216, v130
	v_add_f32_e32 v130, v217, v130
	v_add_f32_e32 v130, v236, v130
	v_exp_f32_e32 v238, v7
	v_exp_f32_e32 v240, v4
	v_cvt_pk_bf16_f32 v4, v196, v197
	v_cvt_pk_bf16_f32 v7, v140, v141
	v_add_u32_e32 v140, s20, v227
	v_add_u32_e32 v196, s20, v229
	v_add_u32_e32 v197, s20, v228
	v_exp_f32_e32 v237, v6
	v_add_f32_e32 v6, v16, v130
	s_cmp_eq_u32 s98, 0
	s_cbranch_scc1 .Lnsa_nomid_c
	s_waitcnt vmcnt(0) lgkmcnt(0)
	s_barrier
	s_mov_b32 s99, 1
.Lnsa_nomid_c:
	ds_read_b64_tr_b16 v[130:131], v140 offset:8192
	ds_read_b64_tr_b16 v[132:133], v196 offset:8192
	ds_read_b64_tr_b16 v[134:135], v197 offset:8192
	v_exp_f32_e32 v17, v17
	v_exp_f32_e32 v241, v5
	v_cvt_pk_bf16_f32 v5, v194, v195
	v_cndmask_b32_e64 v4, 0, v4, s[4:5]
	v_add_f32_e32 v6, v17, v6
	v_add_f32_e32 v6, v237, v6
	v_add_f32_e32 v239, v238, v6
	v_cvt_pk_bf16_f32 v6, v192, v193
	v_cndmask_b32_e64 v5, 0, v5, s[4:5]
	v_cndmask_b32_e64 v6, 0, v6, s[4:5]
	v_cndmask_b32_e64 v7, 0, v7, s[4:5]
	v_add_u32_e32 v210, s20, v230
	ds_read_b64_tr_b16 v[136:137], v210 offset:8192
	ds_read_b64_tr_b16 v[138:139], v140 offset:10240
	ds_read_b64_tr_b16 v[192:193], v140 offset:12288
	ds_read_b64_tr_b16 v[200:201], v140 offset:14336
	ds_read_b64_tr_b16 v[140:141], v196 offset:10240
	ds_read_b64_tr_b16 v[194:195], v196 offset:12288
	ds_read_b64_tr_b16 v[202:203], v196 offset:14336
	s_waitcnt lgkmcnt(8)
	v_mfma_f32_32x32x16_bf16 v[50:65], v[130:133], v[4:7], v[50:65]
	v_cvt_pk_bf16_f32 v196, v204, v205
	ds_read_b64_tr_b16 v[130:131], v197 offset:10240
	ds_read_b64_tr_b16 v[204:205], v197 offset:12288
	ds_read_b64_tr_b16 v[208:209], v197 offset:14336
	ds_read_b64_tr_b16 v[132:133], v210 offset:10240
	ds_read_b64_tr_b16 v[206:207], v210 offset:12288
	ds_read_b64_tr_b16 v[210:211], v210 offset:14336
	v_exp_f32_e32 v14, v14
	v_exp_f32_e32 v15, v15
	v_exp_f32_e32 v8, v8
	v_exp_f32_e32 v9, v9
	v_exp_f32_e32 v10, v10
	s_waitcnt lgkmcnt(12)
	v_mfma_f32_32x32x16_bf16 v[66:81], v[134:137], v[4:7], v[66:81]
	v_cvt_pk_bf16_f32 v5, v199, v212
	v_cvt_pk_bf16_f32 v6, v213, v214
	v_cvt_pk_bf16_f32 v7, v215, v216
	v_cndmask_b32_e64 v4, 0, v196, s[4:5]
	v_cndmask_b32_e64 v5, 0, v5, s[4:5]
	v_cndmask_b32_e64 v6, 0, v6, s[4:5]
	v_cndmask_b32_e64 v7, 0, v7, s[4:5]
	v_add_f32_e32 v134, v240, v239
	v_add_f32_e32 v134, v241, v134
	s_waitcnt lgkmcnt(8)
	v_mfma_f32_32x32x16_bf16 v[50:65], v[138:141], v[4:7], v[50:65]
	v_add_f32_e32 v134, v14, v134
	v_add_f32_e32 v134, v15, v134
	v_exp_f32_e32 v11, v11
	v_exp_f32_e32 v12, v12
	v_exp_f32_e32 v13, v13
	v_cvt_pk_bf16_f32 v14, v14, v15
	s_waitcnt lgkmcnt(2)
	v_mfma_f32_32x32x16_bf16 v[66:81], v[130:133], v[4:7], v[66:81]
	v_cvt_pk_bf16_f32 v4, v217, v236
	v_cvt_pk_bf16_f32 v5, v16, v17
	v_cvt_pk_bf16_f32 v6, v237, v238
	v_cvt_pk_bf16_f32 v7, v240, v241
	v_cndmask_b32_e64 v4, 0, v4, s[4:5]
	v_cndmask_b32_e64 v5, 0, v5, s[4:5]
	v_cndmask_b32_e64 v6, 0, v6, s[4:5]
	v_cndmask_b32_e64 v7, 0, v7, s[4:5]
	v_add_f32_e32 v16, v8, v134
	s_nop 0
	v_mfma_f32_32x32x16_bf16 v[50:65], v[192:195], v[4:7], v[50:65]
	s_waitcnt lgkmcnt(1)
	v_mfma_f32_32x32x16_bf16 v[66:81], v[204:207], v[4:7], v[66:81]
	v_cvt_pk_bf16_f32 v5, v8, v9
	v_add_f32_e32 v8, v9, v16
	v_add_f32_e32 v8, v10, v8
	v_add_f32_e32 v8, v11, v8
	v_add_f32_e32 v8, v12, v8
	v_cvt_pk_bf16_f32 v6, v10, v11
	v_cvt_pk_bf16_f32 v7, v12, v13
	v_add_f32_e32 v8, v13, v8
	v_cndmask_b32_e64 v4, 0, v14, s[4:5]
	v_cndmask_b32_e64 v5, 0, v5, s[4:5]
	v_cndmask_b32_e64 v6, 0, v6, s[4:5]
	v_cndmask_b32_e64 v7, 0, v7, s[4:5]
	v_cndmask_b32_e64 v8, 0, v8, s[4:5]
	v_add_f32_e32 v16, v198, v8
	v_mfma_f32_32x32x16_bf16 v[50:65], v[200:203], v[4:7], v[50:65]
	s_waitcnt lgkmcnt(0)
	v_mfma_f32_32x32x16_bf16 v[66:81], v[208:211], v[4:7], v[66:81]
	s_cbranch_execz .LBB0_2064
	s_branch .LBB0_2069
